# hand-written MLA q up-projection epilogue: rotary tables preloaded once per tile, chunk kinds resolved once, dwordx4 stores
# speedup vs baseline: 1.0129x; 1.0035x over previous
.LBB0_619:
	v_lshl_add_u32 v145, s24, 8, v155
	v_readlane_b32 s20, v255, 31
	v_readlane_b32 s21, v255, 32
	v_lshlrev_b32_e32 v142, 2, v145
	s_nop 7
	global_load_dword v158, v142, s[20:21] offset:0
	global_load_dword v159, v142, s[20:21] offset:64
	global_load_dword v160, v142, s[20:21] offset:128
	global_load_dword v161, v142, s[20:21] offset:192
	global_load_dword v162, v142, s[20:21] offset:512
	global_load_dword v163, v142, s[20:21] offset:576
	global_load_dword v164, v142, s[20:21] offset:640
	global_load_dword v165, v142, s[20:21] offset:704
	v_and_b32_e32 v178, 4, v134
	v_mul_u32_u24_e32 v178, 6, v178
	v_lshl_add_u32 v178, v134, 1, v178
	v_mul_u32_u24_e32 v143, 0x300, v145
	v_add_u32_e32 v143, v143, v178
	v_lshlrev_b32_e32 v144, 2, v232
	s_lshl_b32 s52, s22, 4
	s_lshr_b32 s53, s66, 4
	s_add_i32 s52, s52, s53
	s_cmpk_lt_i32 s24, 0x80
	s_cselect_b32 s27, 1, 0
	s_add_i32 s53, s52, 0
	s_cmpk_lt_i32 s53, 24
	s_cselect_b32 s46, 1, 0
	s_add_i32 s53, s52, 0
	s_mul_i32 s54, s53, 43
	s_lshr_b32 s54, s54, 8
	s_mul_i32 s54, s54, 6
	s_sub_i32 s54, s53, s54
	s_sub_i32 s54, s54, 3
	s_max_i32 s54, s54, 0
	s_mul_i32 s42, s54, s27
	s_add_i32 s53, s52, 1
	s_mul_i32 s54, s53, 43
	s_lshr_b32 s54, s54, 8
	s_mul_i32 s54, s54, 6
	s_sub_i32 s54, s53, s54
	s_sub_i32 s54, s54, 3
	s_max_i32 s54, s54, 0
	s_mul_i32 s43, s54, s27
	s_add_i32 s53, s52, 8
	s_cmpk_lt_i32 s53, 24
	s_cselect_b32 s47, 1, 0
	s_add_i32 s53, s52, 8
	s_mul_i32 s54, s53, 43
	s_lshr_b32 s54, s54, 8
	s_mul_i32 s54, s54, 6
	s_sub_i32 s54, s53, s54
	s_sub_i32 s54, s54, 3
	s_max_i32 s54, s54, 0
	s_mul_i32 s44, s54, s27
	s_add_i32 s53, s52, 9
	s_mul_i32 s54, s53, 43
	s_lshr_b32 s54, s54, 8
	s_mul_i32 s54, s54, 6
	s_sub_i32 s54, s53, s54
	s_sub_i32 s54, s54, 3
	s_max_i32 s54, s54, 0
	s_mul_i32 s45, s54, s27
	s_lshl_b32 s52, s22, 9
	s_lshl_b32 s53, s66, 1
	s_add_i32 s52, s52, s53
	s_add_u32 s48, s94, s52
	s_addc_u32 s49, s95, 0
	s_cmp_eq_u32 s27, 0
	s_cbranch_scc1 .Luq_notab
	s_and_b32 s52, s24, 15
	s_lshl_b32 s52, s52, 8
	v_add_u32_e32 v98, s52, v155
	v_lshrrev_b32_e32 v98, 6, v98
	v_lshlrev_b32_e32 v98, 6, v98
	v_lshl_add_u64 v[178:179], v[98:99], 0, v[136:137]
	global_load_dwordx4 v[166:169], v[178:179], off
	global_load_dwordx4 v[170:173], v[178:179], off offset:32
	v_add_u32_e32 v98, s52, v155
	v_add_u32_e32 v98, 0x80, v98
	v_lshrrev_b32_e32 v98, 6, v98
	v_lshlrev_b32_e32 v98, 6, v98
	v_lshl_add_u64 v[178:179], v[98:99], 0, v[136:137]
	global_load_dwordx4 v[174:177], v[178:179], off
	global_load_dwordx4 v[188:191], v[178:179], off offset:32
	v_and_b32_e32 v98, 15, v155
	v_lshlrev_b32_e32 v98, 6, v98
	v_lshl_add_u64 v[178:179], v[98:99], 0, v[136:137]
	global_load_dwordx4 v[192:195], v[178:179], off
	global_load_dwordx4 v[208:211], v[178:179], off offset:32
	v_and_b32_e32 v98, 15, v155
	v_add_u32_e32 v98, 16, v98
	v_lshlrev_b32_e32 v98, 6, v98
	v_lshl_add_u64 v[178:179], v[98:99], 0, v[136:137]
	global_load_dwordx4 v[196:199], v[178:179], off
	global_load_dwordx4 v[212:215], v[178:179], off offset:32
	v_and_b32_e32 v98, 15, v155
	v_add_u32_e32 v98, 32, v98
	v_lshlrev_b32_e32 v98, 6, v98
	v_lshl_add_u64 v[178:179], v[98:99], 0, v[136:137]
	global_load_dwordx4 v[200:203], v[178:179], off
	global_load_dwordx4 v[216:219], v[178:179], off offset:32
	v_and_b32_e32 v98, 15, v155
	v_add_u32_e32 v98, 48, v98
	v_lshlrev_b32_e32 v98, 6, v98
	v_lshl_add_u64 v[178:179], v[98:99], 0, v[136:137]
	global_load_dwordx4 v[204:207], v[178:179], off
	global_load_dwordx4 v[238:241], v[178:179], off offset:32
	s_waitcnt vmcnt(0)
	v_cndmask_b32_e64 v170, v170, -v170, s[38:39]
	v_cndmask_b32_e64 v171, v171, -v171, s[38:39]
	v_cndmask_b32_e64 v172, v172, -v172, s[38:39]
	v_cndmask_b32_e64 v173, v173, -v173, s[38:39]
	v_cndmask_b32_e64 v188, v188, -v188, s[38:39]
	v_cndmask_b32_e64 v189, v189, -v189, s[38:39]
	v_cndmask_b32_e64 v190, v190, -v190, s[38:39]
	v_cndmask_b32_e64 v191, v191, -v191, s[38:39]
	v_cndmask_b32_e64 v208, v208, -v208, s[38:39]
	v_cndmask_b32_e64 v209, v209, -v209, s[38:39]
	v_cndmask_b32_e64 v210, v210, -v210, s[38:39]
	v_cndmask_b32_e64 v211, v211, -v211, s[38:39]
	v_cndmask_b32_e64 v212, v212, -v212, s[38:39]
	v_cndmask_b32_e64 v213, v213, -v213, s[38:39]
	v_cndmask_b32_e64 v214, v214, -v214, s[38:39]
	v_cndmask_b32_e64 v215, v215, -v215, s[38:39]
	v_cndmask_b32_e64 v216, v216, -v216, s[38:39]
	v_cndmask_b32_e64 v217, v217, -v217, s[38:39]
	v_cndmask_b32_e64 v218, v218, -v218, s[38:39]
	v_cndmask_b32_e64 v219, v219, -v219, s[38:39]
	v_cndmask_b32_e64 v238, v238, -v238, s[38:39]
	v_cndmask_b32_e64 v239, v239, -v239, s[38:39]
	v_cndmask_b32_e64 v240, v240, -v240, s[38:39]
	v_cndmask_b32_e64 v241, v241, -v241, s[38:39]
.Luq_notab:
	s_waitcnt vmcnt(0)
	v_fmamk_f32 v158, v158, 0x3b800000, v223
	v_cmp_gt_f32_e32 vcc, s29, v158
	v_mul_f32_e32 v145, 0x4b800000, v158
	s_nop 0
	v_cndmask_b32_e32 v158, v158, v145, vcc
	v_rsq_f32_e32 v158, v158
	s_nop 0
	v_mul_f32_e32 v145, 0x45800000, v158
	v_cndmask_b32_e32 v158, v158, v145, vcc
	v_mul_f32_e32 v158, 0x3e16c740, v158
	v_fmamk_f32 v159, v159, 0x3b800000, v223
	v_cmp_gt_f32_e32 vcc, s29, v159
	v_mul_f32_e32 v145, 0x4b800000, v159
	s_nop 0
	v_cndmask_b32_e32 v159, v159, v145, vcc
	v_rsq_f32_e32 v159, v159
	s_nop 0
	v_mul_f32_e32 v145, 0x45800000, v159
	v_cndmask_b32_e32 v159, v159, v145, vcc
	v_mul_f32_e32 v159, 0x3e16c740, v159
	v_fmamk_f32 v160, v160, 0x3b800000, v223
	v_cmp_gt_f32_e32 vcc, s29, v160
	v_mul_f32_e32 v145, 0x4b800000, v160
	s_nop 0
	v_cndmask_b32_e32 v160, v160, v145, vcc
	v_rsq_f32_e32 v160, v160
	s_nop 0
	v_mul_f32_e32 v145, 0x45800000, v160
	v_cndmask_b32_e32 v160, v160, v145, vcc
	v_mul_f32_e32 v160, 0x3e16c740, v160
	v_fmamk_f32 v161, v161, 0x3b800000, v223
	v_cmp_gt_f32_e32 vcc, s29, v161
	v_mul_f32_e32 v145, 0x4b800000, v161
	s_nop 0
	v_cndmask_b32_e32 v161, v161, v145, vcc
	v_rsq_f32_e32 v161, v161
	s_nop 0
	v_mul_f32_e32 v145, 0x45800000, v161
	v_cndmask_b32_e32 v161, v161, v145, vcc
	v_mul_f32_e32 v161, 0x3e16c740, v161
	v_fmamk_f32 v162, v162, 0x3b800000, v223
	v_cmp_gt_f32_e32 vcc, s29, v162
	v_mul_f32_e32 v145, 0x4b800000, v162
	s_nop 0
	v_cndmask_b32_e32 v162, v162, v145, vcc
	v_rsq_f32_e32 v162, v162
	s_nop 0
	v_mul_f32_e32 v145, 0x45800000, v162
	v_cndmask_b32_e32 v162, v162, v145, vcc
	v_mul_f32_e32 v162, 0x3e16c740, v162
	v_fmamk_f32 v163, v163, 0x3b800000, v223
	v_cmp_gt_f32_e32 vcc, s29, v163
	v_mul_f32_e32 v145, 0x4b800000, v163
	s_nop 0
	v_cndmask_b32_e32 v163, v163, v145, vcc
	v_rsq_f32_e32 v163, v163
	s_nop 0
	v_mul_f32_e32 v145, 0x45800000, v163
	v_cndmask_b32_e32 v163, v163, v145, vcc
	v_mul_f32_e32 v163, 0x3e16c740, v163
	v_fmamk_f32 v164, v164, 0x3b800000, v223
	v_cmp_gt_f32_e32 vcc, s29, v164
	v_mul_f32_e32 v145, 0x4b800000, v164
	s_nop 0
	v_cndmask_b32_e32 v164, v164, v145, vcc
	v_rsq_f32_e32 v164, v164
	s_nop 0
	v_mul_f32_e32 v145, 0x45800000, v164
	v_cndmask_b32_e32 v164, v164, v145, vcc
	v_mul_f32_e32 v164, 0x3e16c740, v164
	v_fmamk_f32 v165, v165, 0x3b800000, v223
	v_cmp_gt_f32_e32 vcc, s29, v165
	v_mul_f32_e32 v145, 0x4b800000, v165
	s_nop 0
	v_cndmask_b32_e32 v165, v165, v145, vcc
	v_rsq_f32_e32 v165, v165
	s_nop 0
	v_mul_f32_e32 v145, 0x45800000, v165
	v_cndmask_b32_e32 v165, v165, v145, vcc
	v_mul_f32_e32 v165, 0x3e16c740, v165
	s_mov_b32 s50, s48
	s_mov_b32 s51, s49
	s_cmp_eq_u32 s46, 0
	s_cbranch_scc1 .Luq_skipbj_0_0
	v_pk_mul_f32 v[128:129], v[128:129], v[158:159] op_sel_hi:[1,0]
	v_pk_mul_f32 v[130:131], v[130:131], v[158:159] op_sel_hi:[1,0]
	s_cmp_eq_u32 s42, 0
	s_cbranch_scc1 .Luq_plain_1
	ds_bpermute_b32 v242, v144, v128
	ds_bpermute_b32 v243, v144, v129
	ds_bpermute_b32 v244, v144, v130
	ds_bpermute_b32 v245, v144, v131
	s_cmp_eq_u32 s42, 1
	s_cbranch_scc0 .Luq_col_1
	s_waitcnt lgkmcnt(0)
	v_pk_mul_f32 v[242:243], v[242:243], v[170:171]
	v_pk_mul_f32 v[244:245], v[244:245], v[172:173]
	v_pk_fma_f32 v[128:129], v[128:129], v[166:167], v[242:243]
	v_pk_fma_f32 v[130:131], v[130:131], v[168:169], v[244:245]
	s_branch .Luq_plain_1
.Luq_col_1:
	s_waitcnt lgkmcnt(0)
	v_pk_mul_f32 v[242:243], v[242:243], v[208:209]
	v_pk_mul_f32 v[244:245], v[244:245], v[210:211]
	v_pk_fma_f32 v[128:129], v[128:129], v[192:193], v[242:243]
	v_pk_fma_f32 v[130:131], v[130:131], v[194:195], v[244:245]
.Luq_plain_1:
	v_pk_mul_f32 v[124:125], v[124:125], v[158:159] op_sel_hi:[1,0]
	v_pk_mul_f32 v[126:127], v[126:127], v[158:159] op_sel_hi:[1,0]
	s_cmp_eq_u32 s43, 0
	s_cbranch_scc1 .Luq_plain_2
	ds_bpermute_b32 v242, v144, v124
	ds_bpermute_b32 v243, v144, v125
	ds_bpermute_b32 v244, v144, v126
	ds_bpermute_b32 v245, v144, v127
	s_cmp_eq_u32 s43, 1
	s_cbranch_scc0 .Luq_col_2
	s_waitcnt lgkmcnt(0)
	v_pk_mul_f32 v[242:243], v[242:243], v[170:171]
	v_pk_mul_f32 v[244:245], v[244:245], v[172:173]
	v_pk_fma_f32 v[124:125], v[124:125], v[166:167], v[242:243]
	v_pk_fma_f32 v[126:127], v[126:127], v[168:169], v[244:245]
	s_branch .Luq_plain_2
.Luq_col_2:
	s_waitcnt lgkmcnt(0)
	v_pk_mul_f32 v[242:243], v[242:243], v[208:209]
	v_pk_mul_f32 v[244:245], v[244:245], v[210:211]
	v_pk_fma_f32 v[124:125], v[124:125], v[192:193], v[242:243]
	v_pk_fma_f32 v[126:127], v[126:127], v[194:195], v[244:245]
.Luq_plain_2:
	v_cvt_pk_bf16_f32 v128, v128, v129
	v_cvt_pk_bf16_f32 v129, v130, v131
	v_cvt_pk_bf16_f32 v130, v124, v125
	v_cvt_pk_bf16_f32 v131, v126, v127
	s_nop 1
	v_permlane16_swap_b32 v128, v130
	v_permlane16_swap_b32 v129, v131
	global_store_dwordx4 v143, v[128:131], s[50:51]
.Luq_skipbj_0_0:
	s_cmp_eq_u32 s47, 0
	s_cbranch_scc1 .Luq_skipbj_0_1
	v_pk_mul_f32 v[120:121], v[120:121], v[158:159] op_sel_hi:[1,0]
	v_pk_mul_f32 v[122:123], v[122:123], v[158:159] op_sel_hi:[1,0]
	s_cmp_eq_u32 s44, 0
	s_cbranch_scc1 .Luq_plain_3
	ds_bpermute_b32 v242, v144, v120
	ds_bpermute_b32 v243, v144, v121
	ds_bpermute_b32 v244, v144, v122
	ds_bpermute_b32 v245, v144, v123
	s_cmp_eq_u32 s44, 1
	s_cbranch_scc0 .Luq_col_3
	s_waitcnt lgkmcnt(0)
	v_pk_mul_f32 v[242:243], v[242:243], v[170:171]
	v_pk_mul_f32 v[244:245], v[244:245], v[172:173]
	v_pk_fma_f32 v[120:121], v[120:121], v[166:167], v[242:243]
	v_pk_fma_f32 v[122:123], v[122:123], v[168:169], v[244:245]
	s_branch .Luq_plain_3
.Luq_col_3:
	s_waitcnt lgkmcnt(0)
	v_pk_mul_f32 v[242:243], v[242:243], v[208:209]
	v_pk_mul_f32 v[244:245], v[244:245], v[210:211]
	v_pk_fma_f32 v[120:121], v[120:121], v[192:193], v[242:243]
	v_pk_fma_f32 v[122:123], v[122:123], v[194:195], v[244:245]
.Luq_plain_3:
	v_pk_mul_f32 v[116:117], v[116:117], v[158:159] op_sel_hi:[1,0]
	v_pk_mul_f32 v[118:119], v[118:119], v[158:159] op_sel_hi:[1,0]
	s_cmp_eq_u32 s45, 0
	s_cbranch_scc1 .Luq_plain_4
	ds_bpermute_b32 v242, v144, v116
	ds_bpermute_b32 v243, v144, v117
	ds_bpermute_b32 v244, v144, v118
	ds_bpermute_b32 v245, v144, v119
	s_cmp_eq_u32 s45, 1
	s_cbranch_scc0 .Luq_col_4
	s_waitcnt lgkmcnt(0)
	v_pk_mul_f32 v[242:243], v[242:243], v[170:171]
	v_pk_mul_f32 v[244:245], v[244:245], v[172:173]
	v_pk_fma_f32 v[116:117], v[116:117], v[166:167], v[242:243]
	v_pk_fma_f32 v[118:119], v[118:119], v[168:169], v[244:245]
	s_branch .Luq_plain_4
.Luq_col_4:
	s_waitcnt lgkmcnt(0)
	v_pk_mul_f32 v[242:243], v[242:243], v[208:209]
	v_pk_mul_f32 v[244:245], v[244:245], v[210:211]
	v_pk_fma_f32 v[116:117], v[116:117], v[192:193], v[242:243]
	v_pk_fma_f32 v[118:119], v[118:119], v[194:195], v[244:245]
.Luq_plain_4:
	v_cvt_pk_bf16_f32 v120, v120, v121
	v_cvt_pk_bf16_f32 v121, v122, v123
	v_cvt_pk_bf16_f32 v122, v116, v117
	v_cvt_pk_bf16_f32 v123, v118, v119
	s_nop 1
	v_permlane16_swap_b32 v120, v122
	v_permlane16_swap_b32 v121, v123
	global_store_dwordx4 v143, v[120:123], s[50:51] offset:256
.Luq_skipbj_0_1:
	s_add_u32 s50, s48, 0x3000
	s_addc_u32 s51, s49, 0
	s_cmp_eq_u32 s46, 0
	s_cbranch_scc1 .Luq_skipbj_1_0
	v_pk_mul_f32 v[112:113], v[112:113], v[158:159] op_sel:[0,1] op_sel_hi:[1,1]
	v_pk_mul_f32 v[114:115], v[114:115], v[158:159] op_sel:[0,1] op_sel_hi:[1,1]
	s_cmp_eq_u32 s42, 0
	s_cbranch_scc1 .Luq_plain_5
	ds_bpermute_b32 v242, v144, v112
	ds_bpermute_b32 v243, v144, v113
	ds_bpermute_b32 v244, v144, v114
	ds_bpermute_b32 v245, v144, v115
	s_cmp_eq_u32 s42, 1
	s_cbranch_scc0 .Luq_col_5
	s_waitcnt lgkmcnt(0)
	v_pk_mul_f32 v[242:243], v[242:243], v[170:171]
	v_pk_mul_f32 v[244:245], v[244:245], v[172:173]
	v_pk_fma_f32 v[112:113], v[112:113], v[166:167], v[242:243]
	v_pk_fma_f32 v[114:115], v[114:115], v[168:169], v[244:245]
	s_branch .Luq_plain_5
.Luq_col_5:
	s_waitcnt lgkmcnt(0)
	v_pk_mul_f32 v[242:243], v[242:243], v[212:213]
	v_pk_mul_f32 v[244:245], v[244:245], v[214:215]
	v_pk_fma_f32 v[112:113], v[112:113], v[196:197], v[242:243]
	v_pk_fma_f32 v[114:115], v[114:115], v[198:199], v[244:245]
.Luq_plain_5:
	v_pk_mul_f32 v[108:109], v[108:109], v[158:159] op_sel:[0,1] op_sel_hi:[1,1]
	v_pk_mul_f32 v[110:111], v[110:111], v[158:159] op_sel:[0,1] op_sel_hi:[1,1]
	s_cmp_eq_u32 s43, 0
	s_cbranch_scc1 .Luq_plain_6
	ds_bpermute_b32 v242, v144, v108
	ds_bpermute_b32 v243, v144, v109
	ds_bpermute_b32 v244, v144, v110
	ds_bpermute_b32 v245, v144, v111
	s_cmp_eq_u32 s43, 1
	s_cbranch_scc0 .Luq_col_6
	s_waitcnt lgkmcnt(0)
	v_pk_mul_f32 v[242:243], v[242:243], v[170:171]
	v_pk_mul_f32 v[244:245], v[244:245], v[172:173]
	v_pk_fma_f32 v[108:109], v[108:109], v[166:167], v[242:243]
	v_pk_fma_f32 v[110:111], v[110:111], v[168:169], v[244:245]
	s_branch .Luq_plain_6
.Luq_col_6:
	s_waitcnt lgkmcnt(0)
	v_pk_mul_f32 v[242:243], v[242:243], v[212:213]
	v_pk_mul_f32 v[244:245], v[244:245], v[214:215]
	v_pk_fma_f32 v[108:109], v[108:109], v[196:197], v[242:243]
	v_pk_fma_f32 v[110:111], v[110:111], v[198:199], v[244:245]
.Luq_plain_6:
	v_cvt_pk_bf16_f32 v112, v112, v113
	v_cvt_pk_bf16_f32 v113, v114, v115
	v_cvt_pk_bf16_f32 v114, v108, v109
	v_cvt_pk_bf16_f32 v115, v110, v111
	s_nop 1
	v_permlane16_swap_b32 v112, v114
	v_permlane16_swap_b32 v113, v115
	global_store_dwordx4 v143, v[112:115], s[50:51]
.Luq_skipbj_1_0:
	s_cmp_eq_u32 s47, 0
	s_cbranch_scc1 .Luq_skipbj_1_1
	v_pk_mul_f32 v[104:105], v[104:105], v[158:159] op_sel:[0,1] op_sel_hi:[1,1]
	v_pk_mul_f32 v[106:107], v[106:107], v[158:159] op_sel:[0,1] op_sel_hi:[1,1]
	s_cmp_eq_u32 s44, 0
	s_cbranch_scc1 .Luq_plain_7
	ds_bpermute_b32 v242, v144, v104
	ds_bpermute_b32 v243, v144, v105
	ds_bpermute_b32 v244, v144, v106
	ds_bpermute_b32 v245, v144, v107
	s_cmp_eq_u32 s44, 1
	s_cbranch_scc0 .Luq_col_7
	s_waitcnt lgkmcnt(0)
	v_pk_mul_f32 v[242:243], v[242:243], v[170:171]
	v_pk_mul_f32 v[244:245], v[244:245], v[172:173]
	v_pk_fma_f32 v[104:105], v[104:105], v[166:167], v[242:243]
	v_pk_fma_f32 v[106:107], v[106:107], v[168:169], v[244:245]
	s_branch .Luq_plain_7
.Luq_col_7:
	s_waitcnt lgkmcnt(0)
	v_pk_mul_f32 v[242:243], v[242:243], v[212:213]
	v_pk_mul_f32 v[244:245], v[244:245], v[214:215]
	v_pk_fma_f32 v[104:105], v[104:105], v[196:197], v[242:243]
	v_pk_fma_f32 v[106:107], v[106:107], v[198:199], v[244:245]
.Luq_plain_7:
	v_pk_mul_f32 v[100:101], v[100:101], v[158:159] op_sel:[0,1] op_sel_hi:[1,1]
	v_pk_mul_f32 v[102:103], v[102:103], v[158:159] op_sel:[0,1] op_sel_hi:[1,1]
	s_cmp_eq_u32 s45, 0
	s_cbranch_scc1 .Luq_plain_8
	ds_bpermute_b32 v242, v144, v100
	ds_bpermute_b32 v243, v144, v101
	ds_bpermute_b32 v244, v144, v102
	ds_bpermute_b32 v245, v144, v103
	s_cmp_eq_u32 s45, 1
	s_cbranch_scc0 .Luq_col_8
	s_waitcnt lgkmcnt(0)
	v_pk_mul_f32 v[242:243], v[242:243], v[170:171]
	v_pk_mul_f32 v[244:245], v[244:245], v[172:173]
	v_pk_fma_f32 v[100:101], v[100:101], v[166:167], v[242:243]
	v_pk_fma_f32 v[102:103], v[102:103], v[168:169], v[244:245]
	s_branch .Luq_plain_8
.Luq_col_8:
	s_waitcnt lgkmcnt(0)
	v_pk_mul_f32 v[242:243], v[242:243], v[212:213]
	v_pk_mul_f32 v[244:245], v[244:245], v[214:215]
	v_pk_fma_f32 v[100:101], v[100:101], v[196:197], v[242:243]
	v_pk_fma_f32 v[102:103], v[102:103], v[198:199], v[244:245]
.Luq_plain_8:
	v_cvt_pk_bf16_f32 v104, v104, v105
	v_cvt_pk_bf16_f32 v105, v106, v107
	v_cvt_pk_bf16_f32 v106, v100, v101
	v_cvt_pk_bf16_f32 v107, v102, v103
	s_nop 1
	v_permlane16_swap_b32 v104, v106
	v_permlane16_swap_b32 v105, v107
	global_store_dwordx4 v143, v[104:107], s[50:51] offset:256
.Luq_skipbj_1_1:
	s_add_u32 s50, s48, 0x6000
	s_addc_u32 s51, s49, 0
	s_cmp_eq_u32 s46, 0
	s_cbranch_scc1 .Luq_skipbj_2_0
	v_pk_mul_f32 v[92:93], v[92:93], v[160:161] op_sel_hi:[1,0]
	v_pk_mul_f32 v[94:95], v[94:95], v[160:161] op_sel_hi:[1,0]
	s_cmp_eq_u32 s42, 0
	s_cbranch_scc1 .Luq_plain_9
	ds_bpermute_b32 v242, v144, v92
	ds_bpermute_b32 v243, v144, v93
	ds_bpermute_b32 v244, v144, v94
	ds_bpermute_b32 v245, v144, v95
	s_cmp_eq_u32 s42, 1
	s_cbranch_scc0 .Luq_col_9
	s_waitcnt lgkmcnt(0)
	v_pk_mul_f32 v[242:243], v[242:243], v[170:171]
	v_pk_mul_f32 v[244:245], v[244:245], v[172:173]
	v_pk_fma_f32 v[92:93], v[92:93], v[166:167], v[242:243]
	v_pk_fma_f32 v[94:95], v[94:95], v[168:169], v[244:245]
	s_branch .Luq_plain_9
.Luq_col_9:
	s_waitcnt lgkmcnt(0)
	v_pk_mul_f32 v[242:243], v[242:243], v[216:217]
	v_pk_mul_f32 v[244:245], v[244:245], v[218:219]
	v_pk_fma_f32 v[92:93], v[92:93], v[200:201], v[242:243]
	v_pk_fma_f32 v[94:95], v[94:95], v[202:203], v[244:245]
.Luq_plain_9:
	v_pk_mul_f32 v[88:89], v[88:89], v[160:161] op_sel_hi:[1,0]
	v_pk_mul_f32 v[90:91], v[90:91], v[160:161] op_sel_hi:[1,0]
	s_cmp_eq_u32 s43, 0
	s_cbranch_scc1 .Luq_plain_10
	ds_bpermute_b32 v242, v144, v88
	ds_bpermute_b32 v243, v144, v89
	ds_bpermute_b32 v244, v144, v90
	ds_bpermute_b32 v245, v144, v91
	s_cmp_eq_u32 s43, 1
	s_cbranch_scc0 .Luq_col_10
	s_waitcnt lgkmcnt(0)
	v_pk_mul_f32 v[242:243], v[242:243], v[170:171]
	v_pk_mul_f32 v[244:245], v[244:245], v[172:173]
	v_pk_fma_f32 v[88:89], v[88:89], v[166:167], v[242:243]
	v_pk_fma_f32 v[90:91], v[90:91], v[168:169], v[244:245]
	s_branch .Luq_plain_10
.Luq_col_10:
	s_waitcnt lgkmcnt(0)
	v_pk_mul_f32 v[242:243], v[242:243], v[216:217]
	v_pk_mul_f32 v[244:245], v[244:245], v[218:219]
	v_pk_fma_f32 v[88:89], v[88:89], v[200:201], v[242:243]
	v_pk_fma_f32 v[90:91], v[90:91], v[202:203], v[244:245]
.Luq_plain_10:
	v_cvt_pk_bf16_f32 v92, v92, v93
	v_cvt_pk_bf16_f32 v93, v94, v95
	v_cvt_pk_bf16_f32 v94, v88, v89
	v_cvt_pk_bf16_f32 v95, v90, v91
	s_nop 1
	v_permlane16_swap_b32 v92, v94
	v_permlane16_swap_b32 v93, v95
	global_store_dwordx4 v143, v[92:95], s[50:51]
.Luq_skipbj_2_0:
	s_cmp_eq_u32 s47, 0
	s_cbranch_scc1 .Luq_skipbj_2_1
	v_pk_mul_f32 v[84:85], v[84:85], v[160:161] op_sel_hi:[1,0]
	v_pk_mul_f32 v[86:87], v[86:87], v[160:161] op_sel_hi:[1,0]
	s_cmp_eq_u32 s44, 0
	s_cbranch_scc1 .Luq_plain_11
	ds_bpermute_b32 v242, v144, v84
	ds_bpermute_b32 v243, v144, v85
	ds_bpermute_b32 v244, v144, v86
	ds_bpermute_b32 v245, v144, v87
	s_cmp_eq_u32 s44, 1
	s_cbranch_scc0 .Luq_col_11
	s_waitcnt lgkmcnt(0)
	v_pk_mul_f32 v[242:243], v[242:243], v[170:171]
	v_pk_mul_f32 v[244:245], v[244:245], v[172:173]
	v_pk_fma_f32 v[84:85], v[84:85], v[166:167], v[242:243]
	v_pk_fma_f32 v[86:87], v[86:87], v[168:169], v[244:245]
	s_branch .Luq_plain_11
.Luq_col_11:
	s_waitcnt lgkmcnt(0)
	v_pk_mul_f32 v[242:243], v[242:243], v[216:217]
	v_pk_mul_f32 v[244:245], v[244:245], v[218:219]
	v_pk_fma_f32 v[84:85], v[84:85], v[200:201], v[242:243]
	v_pk_fma_f32 v[86:87], v[86:87], v[202:203], v[244:245]
.Luq_plain_11:
	v_pk_mul_f32 v[80:81], v[80:81], v[160:161] op_sel_hi:[1,0]
	v_pk_mul_f32 v[82:83], v[82:83], v[160:161] op_sel_hi:[1,0]
	s_cmp_eq_u32 s45, 0
	s_cbranch_scc1 .Luq_plain_12
	ds_bpermute_b32 v242, v144, v80
	ds_bpermute_b32 v243, v144, v81
	ds_bpermute_b32 v244, v144, v82
	ds_bpermute_b32 v245, v144, v83
	s_cmp_eq_u32 s45, 1
	s_cbranch_scc0 .Luq_col_12
	s_waitcnt lgkmcnt(0)
	v_pk_mul_f32 v[242:243], v[242:243], v[170:171]
	v_pk_mul_f32 v[244:245], v[244:245], v[172:173]
	v_pk_fma_f32 v[80:81], v[80:81], v[166:167], v[242:243]
	v_pk_fma_f32 v[82:83], v[82:83], v[168:169], v[244:245]
	s_branch .Luq_plain_12
.Luq_col_12:
	s_waitcnt lgkmcnt(0)
	v_pk_mul_f32 v[242:243], v[242:243], v[216:217]
	v_pk_mul_f32 v[244:245], v[244:245], v[218:219]
	v_pk_fma_f32 v[80:81], v[80:81], v[200:201], v[242:243]
	v_pk_fma_f32 v[82:83], v[82:83], v[202:203], v[244:245]
.Luq_plain_12:
	v_cvt_pk_bf16_f32 v84, v84, v85
	v_cvt_pk_bf16_f32 v85, v86, v87
	v_cvt_pk_bf16_f32 v86, v80, v81
	v_cvt_pk_bf16_f32 v87, v82, v83
	s_nop 1
	v_permlane16_swap_b32 v84, v86
	v_permlane16_swap_b32 v85, v87
	global_store_dwordx4 v143, v[84:87], s[50:51] offset:256
.Luq_skipbj_2_1:
	s_add_u32 s50, s48, 0x9000
	s_addc_u32 s51, s49, 0
	s_cmp_eq_u32 s46, 0
	s_cbranch_scc1 .Luq_skipbj_3_0
	v_pk_mul_f32 v[76:77], v[76:77], v[160:161] op_sel:[0,1] op_sel_hi:[1,1]
	v_pk_mul_f32 v[78:79], v[78:79], v[160:161] op_sel:[0,1] op_sel_hi:[1,1]
	s_cmp_eq_u32 s42, 0
	s_cbranch_scc1 .Luq_plain_13
	ds_bpermute_b32 v242, v144, v76
	ds_bpermute_b32 v243, v144, v77
	ds_bpermute_b32 v244, v144, v78
	ds_bpermute_b32 v245, v144, v79
	s_cmp_eq_u32 s42, 1
	s_cbranch_scc0 .Luq_col_13
	s_waitcnt lgkmcnt(0)
	v_pk_mul_f32 v[242:243], v[242:243], v[170:171]
	v_pk_mul_f32 v[244:245], v[244:245], v[172:173]
	v_pk_fma_f32 v[76:77], v[76:77], v[166:167], v[242:243]
	v_pk_fma_f32 v[78:79], v[78:79], v[168:169], v[244:245]
	s_branch .Luq_plain_13
.Luq_col_13:
	s_waitcnt lgkmcnt(0)
	v_pk_mul_f32 v[242:243], v[242:243], v[238:239]
	v_pk_mul_f32 v[244:245], v[244:245], v[240:241]
	v_pk_fma_f32 v[76:77], v[76:77], v[204:205], v[242:243]
	v_pk_fma_f32 v[78:79], v[78:79], v[206:207], v[244:245]
.Luq_plain_13:
	v_pk_mul_f32 v[72:73], v[72:73], v[160:161] op_sel:[0,1] op_sel_hi:[1,1]
	v_pk_mul_f32 v[74:75], v[74:75], v[160:161] op_sel:[0,1] op_sel_hi:[1,1]
	s_cmp_eq_u32 s43, 0
	s_cbranch_scc1 .Luq_plain_14
	ds_bpermute_b32 v242, v144, v72
	ds_bpermute_b32 v243, v144, v73
	ds_bpermute_b32 v244, v144, v74
	ds_bpermute_b32 v245, v144, v75
	s_cmp_eq_u32 s43, 1
	s_cbranch_scc0 .Luq_col_14
	s_waitcnt lgkmcnt(0)
	v_pk_mul_f32 v[242:243], v[242:243], v[170:171]
	v_pk_mul_f32 v[244:245], v[244:245], v[172:173]
	v_pk_fma_f32 v[72:73], v[72:73], v[166:167], v[242:243]
	v_pk_fma_f32 v[74:75], v[74:75], v[168:169], v[244:245]
	s_branch .Luq_plain_14
.Luq_col_14:
	s_waitcnt lgkmcnt(0)
	v_pk_mul_f32 v[242:243], v[242:243], v[238:239]
	v_pk_mul_f32 v[244:245], v[244:245], v[240:241]
	v_pk_fma_f32 v[72:73], v[72:73], v[204:205], v[242:243]
	v_pk_fma_f32 v[74:75], v[74:75], v[206:207], v[244:245]
.Luq_plain_14:
	v_cvt_pk_bf16_f32 v76, v76, v77
	v_cvt_pk_bf16_f32 v77, v78, v79
	v_cvt_pk_bf16_f32 v78, v72, v73
	v_cvt_pk_bf16_f32 v79, v74, v75
	s_nop 1
	v_permlane16_swap_b32 v76, v78
	v_permlane16_swap_b32 v77, v79
	global_store_dwordx4 v143, v[76:79], s[50:51]
.Luq_skipbj_3_0:
	s_cmp_eq_u32 s47, 0
	s_cbranch_scc1 .Luq_skipbj_3_1
	v_pk_mul_f32 v[68:69], v[68:69], v[160:161] op_sel:[0,1] op_sel_hi:[1,1]
	v_pk_mul_f32 v[70:71], v[70:71], v[160:161] op_sel:[0,1] op_sel_hi:[1,1]
	s_cmp_eq_u32 s44, 0
	s_cbranch_scc1 .Luq_plain_15
	ds_bpermute_b32 v242, v144, v68
	ds_bpermute_b32 v243, v144, v69
	ds_bpermute_b32 v244, v144, v70
	ds_bpermute_b32 v245, v144, v71
	s_cmp_eq_u32 s44, 1
	s_cbranch_scc0 .Luq_col_15
	s_waitcnt lgkmcnt(0)
	v_pk_mul_f32 v[242:243], v[242:243], v[170:171]
	v_pk_mul_f32 v[244:245], v[244:245], v[172:173]
	v_pk_fma_f32 v[68:69], v[68:69], v[166:167], v[242:243]
	v_pk_fma_f32 v[70:71], v[70:71], v[168:169], v[244:245]
	s_branch .Luq_plain_15
.Luq_col_15:
	s_waitcnt lgkmcnt(0)
	v_pk_mul_f32 v[242:243], v[242:243], v[238:239]
	v_pk_mul_f32 v[244:245], v[244:245], v[240:241]
	v_pk_fma_f32 v[68:69], v[68:69], v[204:205], v[242:243]
	v_pk_fma_f32 v[70:71], v[70:71], v[206:207], v[244:245]
.Luq_plain_15:
	v_pk_mul_f32 v[64:65], v[64:65], v[160:161] op_sel:[0,1] op_sel_hi:[1,1]
	v_pk_mul_f32 v[66:67], v[66:67], v[160:161] op_sel:[0,1] op_sel_hi:[1,1]
	s_cmp_eq_u32 s45, 0
	s_cbranch_scc1 .Luq_plain_16
	ds_bpermute_b32 v242, v144, v64
	ds_bpermute_b32 v243, v144, v65
	ds_bpermute_b32 v244, v144, v66
	ds_bpermute_b32 v245, v144, v67
	s_cmp_eq_u32 s45, 1
	s_cbranch_scc0 .Luq_col_16
	s_waitcnt lgkmcnt(0)
	v_pk_mul_f32 v[242:243], v[242:243], v[170:171]
	v_pk_mul_f32 v[244:245], v[244:245], v[172:173]
	v_pk_fma_f32 v[64:65], v[64:65], v[166:167], v[242:243]
	v_pk_fma_f32 v[66:67], v[66:67], v[168:169], v[244:245]
	s_branch .Luq_plain_16
.Luq_col_16:
	s_waitcnt lgkmcnt(0)
	v_pk_mul_f32 v[242:243], v[242:243], v[238:239]
	v_pk_mul_f32 v[244:245], v[244:245], v[240:241]
	v_pk_fma_f32 v[64:65], v[64:65], v[204:205], v[242:243]
	v_pk_fma_f32 v[66:67], v[66:67], v[206:207], v[244:245]
.Luq_plain_16:
	v_cvt_pk_bf16_f32 v68, v68, v69
	v_cvt_pk_bf16_f32 v69, v70, v71
	v_cvt_pk_bf16_f32 v70, v64, v65
	v_cvt_pk_bf16_f32 v71, v66, v67
	s_nop 1
	v_permlane16_swap_b32 v68, v70
	v_permlane16_swap_b32 v69, v71
	global_store_dwordx4 v143, v[68:71], s[50:51] offset:256
.Luq_skipbj_3_1:
	s_add_u32 s50, s48, 0x18000
	s_addc_u32 s51, s49, 0
	s_cmp_eq_u32 s46, 0
	s_cbranch_scc1 .Luq_skipbj_4_0
	v_pk_mul_f32 v[60:61], v[60:61], v[162:163] op_sel_hi:[1,0]
	v_pk_mul_f32 v[62:63], v[62:63], v[162:163] op_sel_hi:[1,0]
	s_cmp_eq_u32 s42, 0
	s_cbranch_scc1 .Luq_plain_17
	ds_bpermute_b32 v242, v144, v60
	ds_bpermute_b32 v243, v144, v61
	ds_bpermute_b32 v244, v144, v62
	ds_bpermute_b32 v245, v144, v63
	s_cmp_eq_u32 s42, 1
	s_cbranch_scc0 .Luq_col_17
	s_waitcnt lgkmcnt(0)
	v_pk_mul_f32 v[242:243], v[242:243], v[188:189]
	v_pk_mul_f32 v[244:245], v[244:245], v[190:191]
	v_pk_fma_f32 v[60:61], v[60:61], v[174:175], v[242:243]
	v_pk_fma_f32 v[62:63], v[62:63], v[176:177], v[244:245]
	s_branch .Luq_plain_17
.Luq_col_17:
	s_waitcnt lgkmcnt(0)
	v_pk_mul_f32 v[242:243], v[242:243], v[208:209]
	v_pk_mul_f32 v[244:245], v[244:245], v[210:211]
	v_pk_fma_f32 v[60:61], v[60:61], v[192:193], v[242:243]
	v_pk_fma_f32 v[62:63], v[62:63], v[194:195], v[244:245]
.Luq_plain_17:
	v_pk_mul_f32 v[56:57], v[56:57], v[162:163] op_sel_hi:[1,0]
	v_pk_mul_f32 v[58:59], v[58:59], v[162:163] op_sel_hi:[1,0]
	s_cmp_eq_u32 s43, 0
	s_cbranch_scc1 .Luq_plain_18
	ds_bpermute_b32 v242, v144, v56
	ds_bpermute_b32 v243, v144, v57
	ds_bpermute_b32 v244, v144, v58
	ds_bpermute_b32 v245, v144, v59
	s_cmp_eq_u32 s43, 1
	s_cbranch_scc0 .Luq_col_18
	s_waitcnt lgkmcnt(0)
	v_pk_mul_f32 v[242:243], v[242:243], v[188:189]
	v_pk_mul_f32 v[244:245], v[244:245], v[190:191]
	v_pk_fma_f32 v[56:57], v[56:57], v[174:175], v[242:243]
	v_pk_fma_f32 v[58:59], v[58:59], v[176:177], v[244:245]
	s_branch .Luq_plain_18
.Luq_col_18:
	s_waitcnt lgkmcnt(0)
	v_pk_mul_f32 v[242:243], v[242:243], v[208:209]
	v_pk_mul_f32 v[244:245], v[244:245], v[210:211]
	v_pk_fma_f32 v[56:57], v[56:57], v[192:193], v[242:243]
	v_pk_fma_f32 v[58:59], v[58:59], v[194:195], v[244:245]
.Luq_plain_18:
	v_cvt_pk_bf16_f32 v60, v60, v61
	v_cvt_pk_bf16_f32 v61, v62, v63
	v_cvt_pk_bf16_f32 v62, v56, v57
	v_cvt_pk_bf16_f32 v63, v58, v59
	s_nop 1
	v_permlane16_swap_b32 v60, v62
	v_permlane16_swap_b32 v61, v63
	global_store_dwordx4 v143, v[60:63], s[50:51]
.Luq_skipbj_4_0:
	s_cmp_eq_u32 s47, 0
	s_cbranch_scc1 .Luq_skipbj_4_1
	v_pk_mul_f32 v[52:53], v[52:53], v[162:163] op_sel_hi:[1,0]
	v_pk_mul_f32 v[54:55], v[54:55], v[162:163] op_sel_hi:[1,0]
	s_cmp_eq_u32 s44, 0
	s_cbranch_scc1 .Luq_plain_19
	ds_bpermute_b32 v242, v144, v52
	ds_bpermute_b32 v243, v144, v53
	ds_bpermute_b32 v244, v144, v54
	ds_bpermute_b32 v245, v144, v55
	s_cmp_eq_u32 s44, 1
	s_cbranch_scc0 .Luq_col_19
	s_waitcnt lgkmcnt(0)
	v_pk_mul_f32 v[242:243], v[242:243], v[188:189]
	v_pk_mul_f32 v[244:245], v[244:245], v[190:191]
	v_pk_fma_f32 v[52:53], v[52:53], v[174:175], v[242:243]
	v_pk_fma_f32 v[54:55], v[54:55], v[176:177], v[244:245]
	s_branch .Luq_plain_19
.Luq_col_19:
	s_waitcnt lgkmcnt(0)
	v_pk_mul_f32 v[242:243], v[242:243], v[208:209]
	v_pk_mul_f32 v[244:245], v[244:245], v[210:211]
	v_pk_fma_f32 v[52:53], v[52:53], v[192:193], v[242:243]
	v_pk_fma_f32 v[54:55], v[54:55], v[194:195], v[244:245]
.Luq_plain_19:
	v_pk_mul_f32 v[48:49], v[48:49], v[162:163] op_sel_hi:[1,0]
	v_pk_mul_f32 v[50:51], v[50:51], v[162:163] op_sel_hi:[1,0]
	s_cmp_eq_u32 s45, 0
	s_cbranch_scc1 .Luq_plain_20
	ds_bpermute_b32 v242, v144, v48
	ds_bpermute_b32 v243, v144, v49
	ds_bpermute_b32 v244, v144, v50
	ds_bpermute_b32 v245, v144, v51
	s_cmp_eq_u32 s45, 1
	s_cbranch_scc0 .Luq_col_20
	s_waitcnt lgkmcnt(0)
	v_pk_mul_f32 v[242:243], v[242:243], v[188:189]
	v_pk_mul_f32 v[244:245], v[244:245], v[190:191]
	v_pk_fma_f32 v[48:49], v[48:49], v[174:175], v[242:243]
	v_pk_fma_f32 v[50:51], v[50:51], v[176:177], v[244:245]
	s_branch .Luq_plain_20
.Luq_col_20:
	s_waitcnt lgkmcnt(0)
	v_pk_mul_f32 v[242:243], v[242:243], v[208:209]
	v_pk_mul_f32 v[244:245], v[244:245], v[210:211]
	v_pk_fma_f32 v[48:49], v[48:49], v[192:193], v[242:243]
	v_pk_fma_f32 v[50:51], v[50:51], v[194:195], v[244:245]
.Luq_plain_20:
	v_cvt_pk_bf16_f32 v52, v52, v53
	v_cvt_pk_bf16_f32 v53, v54, v55
	v_cvt_pk_bf16_f32 v54, v48, v49
	v_cvt_pk_bf16_f32 v55, v50, v51
	s_nop 1
	v_permlane16_swap_b32 v52, v54
	v_permlane16_swap_b32 v53, v55
	global_store_dwordx4 v143, v[52:55], s[50:51] offset:256
.Luq_skipbj_4_1:
	s_add_u32 s50, s48, 0x1b000
	s_addc_u32 s51, s49, 0
	s_cmp_eq_u32 s46, 0
	s_cbranch_scc1 .Luq_skipbj_5_0
	v_pk_mul_f32 v[44:45], v[44:45], v[162:163] op_sel:[0,1] op_sel_hi:[1,1]
	v_pk_mul_f32 v[46:47], v[46:47], v[162:163] op_sel:[0,1] op_sel_hi:[1,1]
	s_cmp_eq_u32 s42, 0
	s_cbranch_scc1 .Luq_plain_21
	ds_bpermute_b32 v242, v144, v44
	ds_bpermute_b32 v243, v144, v45
	ds_bpermute_b32 v244, v144, v46
	ds_bpermute_b32 v245, v144, v47
	s_cmp_eq_u32 s42, 1
	s_cbranch_scc0 .Luq_col_21
	s_waitcnt lgkmcnt(0)
	v_pk_mul_f32 v[242:243], v[242:243], v[188:189]
	v_pk_mul_f32 v[244:245], v[244:245], v[190:191]
	v_pk_fma_f32 v[44:45], v[44:45], v[174:175], v[242:243]
	v_pk_fma_f32 v[46:47], v[46:47], v[176:177], v[244:245]
	s_branch .Luq_plain_21
.Luq_col_21:
	s_waitcnt lgkmcnt(0)
	v_pk_mul_f32 v[242:243], v[242:243], v[212:213]
	v_pk_mul_f32 v[244:245], v[244:245], v[214:215]
	v_pk_fma_f32 v[44:45], v[44:45], v[196:197], v[242:243]
	v_pk_fma_f32 v[46:47], v[46:47], v[198:199], v[244:245]
.Luq_plain_21:
	v_pk_mul_f32 v[40:41], v[40:41], v[162:163] op_sel:[0,1] op_sel_hi:[1,1]
	v_pk_mul_f32 v[42:43], v[42:43], v[162:163] op_sel:[0,1] op_sel_hi:[1,1]
	s_cmp_eq_u32 s43, 0
	s_cbranch_scc1 .Luq_plain_22
	ds_bpermute_b32 v242, v144, v40
	ds_bpermute_b32 v243, v144, v41
	ds_bpermute_b32 v244, v144, v42
	ds_bpermute_b32 v245, v144, v43
	s_cmp_eq_u32 s43, 1
	s_cbranch_scc0 .Luq_col_22
	s_waitcnt lgkmcnt(0)
	v_pk_mul_f32 v[242:243], v[242:243], v[188:189]
	v_pk_mul_f32 v[244:245], v[244:245], v[190:191]
	v_pk_fma_f32 v[40:41], v[40:41], v[174:175], v[242:243]
	v_pk_fma_f32 v[42:43], v[42:43], v[176:177], v[244:245]
	s_branch .Luq_plain_22
.Luq_col_22:
	s_waitcnt lgkmcnt(0)
	v_pk_mul_f32 v[242:243], v[242:243], v[212:213]
	v_pk_mul_f32 v[244:245], v[244:245], v[214:215]
	v_pk_fma_f32 v[40:41], v[40:41], v[196:197], v[242:243]
	v_pk_fma_f32 v[42:43], v[42:43], v[198:199], v[244:245]
.Luq_plain_22:
	v_cvt_pk_bf16_f32 v44, v44, v45
	v_cvt_pk_bf16_f32 v45, v46, v47
	v_cvt_pk_bf16_f32 v46, v40, v41
	v_cvt_pk_bf16_f32 v47, v42, v43
	s_nop 1
	v_permlane16_swap_b32 v44, v46
	v_permlane16_swap_b32 v45, v47
	global_store_dwordx4 v143, v[44:47], s[50:51]
.Luq_skipbj_5_0:
	s_cmp_eq_u32 s47, 0
	s_cbranch_scc1 .Luq_skipbj_5_1
	v_pk_mul_f32 v[36:37], v[36:37], v[162:163] op_sel:[0,1] op_sel_hi:[1,1]
	v_pk_mul_f32 v[38:39], v[38:39], v[162:163] op_sel:[0,1] op_sel_hi:[1,1]
	s_cmp_eq_u32 s44, 0
	s_cbranch_scc1 .Luq_plain_23
	ds_bpermute_b32 v242, v144, v36
	ds_bpermute_b32 v243, v144, v37
	ds_bpermute_b32 v244, v144, v38
	ds_bpermute_b32 v245, v144, v39
	s_cmp_eq_u32 s44, 1
	s_cbranch_scc0 .Luq_col_23
	s_waitcnt lgkmcnt(0)
	v_pk_mul_f32 v[242:243], v[242:243], v[188:189]
	v_pk_mul_f32 v[244:245], v[244:245], v[190:191]
	v_pk_fma_f32 v[36:37], v[36:37], v[174:175], v[242:243]
	v_pk_fma_f32 v[38:39], v[38:39], v[176:177], v[244:245]
	s_branch .Luq_plain_23
.Luq_col_23:
	s_waitcnt lgkmcnt(0)
	v_pk_mul_f32 v[242:243], v[242:243], v[212:213]
	v_pk_mul_f32 v[244:245], v[244:245], v[214:215]
	v_pk_fma_f32 v[36:37], v[36:37], v[196:197], v[242:243]
	v_pk_fma_f32 v[38:39], v[38:39], v[198:199], v[244:245]
.Luq_plain_23:
	v_pk_mul_f32 v[32:33], v[32:33], v[162:163] op_sel:[0,1] op_sel_hi:[1,1]
	v_pk_mul_f32 v[34:35], v[34:35], v[162:163] op_sel:[0,1] op_sel_hi:[1,1]
	s_cmp_eq_u32 s45, 0
	s_cbranch_scc1 .Luq_plain_24
	ds_bpermute_b32 v242, v144, v32
	ds_bpermute_b32 v243, v144, v33
	ds_bpermute_b32 v244, v144, v34
	ds_bpermute_b32 v245, v144, v35
	s_cmp_eq_u32 s45, 1
	s_cbranch_scc0 .Luq_col_24
	s_waitcnt lgkmcnt(0)
	v_pk_mul_f32 v[242:243], v[242:243], v[188:189]
	v_pk_mul_f32 v[244:245], v[244:245], v[190:191]
	v_pk_fma_f32 v[32:33], v[32:33], v[174:175], v[242:243]
	v_pk_fma_f32 v[34:35], v[34:35], v[176:177], v[244:245]
	s_branch .Luq_plain_24
.Luq_col_24:
	s_waitcnt lgkmcnt(0)
	v_pk_mul_f32 v[242:243], v[242:243], v[212:213]
	v_pk_mul_f32 v[244:245], v[244:245], v[214:215]
	v_pk_fma_f32 v[32:33], v[32:33], v[196:197], v[242:243]
	v_pk_fma_f32 v[34:35], v[34:35], v[198:199], v[244:245]
.Luq_plain_24:
	v_cvt_pk_bf16_f32 v36, v36, v37
	v_cvt_pk_bf16_f32 v37, v38, v39
	v_cvt_pk_bf16_f32 v38, v32, v33
	v_cvt_pk_bf16_f32 v39, v34, v35
	s_nop 1
	v_permlane16_swap_b32 v36, v38
	v_permlane16_swap_b32 v37, v39
	global_store_dwordx4 v143, v[36:39], s[50:51] offset:256
.Luq_skipbj_5_1:
	s_add_u32 s50, s48, 0x1e000
	s_addc_u32 s51, s49, 0
	s_cmp_eq_u32 s46, 0
	s_cbranch_scc1 .Luq_skipbj_6_0
	v_pk_mul_f32 v[28:29], v[28:29], v[164:165] op_sel_hi:[1,0]
	v_pk_mul_f32 v[30:31], v[30:31], v[164:165] op_sel_hi:[1,0]
	s_cmp_eq_u32 s42, 0
	s_cbranch_scc1 .Luq_plain_25
	ds_bpermute_b32 v242, v144, v28
	ds_bpermute_b32 v243, v144, v29
	ds_bpermute_b32 v244, v144, v30
	ds_bpermute_b32 v245, v144, v31
	s_cmp_eq_u32 s42, 1
	s_cbranch_scc0 .Luq_col_25
	s_waitcnt lgkmcnt(0)
	v_pk_mul_f32 v[242:243], v[242:243], v[188:189]
	v_pk_mul_f32 v[244:245], v[244:245], v[190:191]
	v_pk_fma_f32 v[28:29], v[28:29], v[174:175], v[242:243]
	v_pk_fma_f32 v[30:31], v[30:31], v[176:177], v[244:245]
	s_branch .Luq_plain_25
.Luq_col_25:
	s_waitcnt lgkmcnt(0)
	v_pk_mul_f32 v[242:243], v[242:243], v[216:217]
	v_pk_mul_f32 v[244:245], v[244:245], v[218:219]
	v_pk_fma_f32 v[28:29], v[28:29], v[200:201], v[242:243]
	v_pk_fma_f32 v[30:31], v[30:31], v[202:203], v[244:245]
.Luq_plain_25:
	v_pk_mul_f32 v[24:25], v[24:25], v[164:165] op_sel_hi:[1,0]
	v_pk_mul_f32 v[26:27], v[26:27], v[164:165] op_sel_hi:[1,0]
	s_cmp_eq_u32 s43, 0
	s_cbranch_scc1 .Luq_plain_26
	ds_bpermute_b32 v242, v144, v24
	ds_bpermute_b32 v243, v144, v25
	ds_bpermute_b32 v244, v144, v26
	ds_bpermute_b32 v245, v144, v27
	s_cmp_eq_u32 s43, 1
	s_cbranch_scc0 .Luq_col_26
	s_waitcnt lgkmcnt(0)
	v_pk_mul_f32 v[242:243], v[242:243], v[188:189]
	v_pk_mul_f32 v[244:245], v[244:245], v[190:191]
	v_pk_fma_f32 v[24:25], v[24:25], v[174:175], v[242:243]
	v_pk_fma_f32 v[26:27], v[26:27], v[176:177], v[244:245]
	s_branch .Luq_plain_26
.Luq_col_26:
	s_waitcnt lgkmcnt(0)
	v_pk_mul_f32 v[242:243], v[242:243], v[216:217]
	v_pk_mul_f32 v[244:245], v[244:245], v[218:219]
	v_pk_fma_f32 v[24:25], v[24:25], v[200:201], v[242:243]
	v_pk_fma_f32 v[26:27], v[26:27], v[202:203], v[244:245]
.Luq_plain_26:
	v_cvt_pk_bf16_f32 v28, v28, v29
	v_cvt_pk_bf16_f32 v29, v30, v31
	v_cvt_pk_bf16_f32 v30, v24, v25
	v_cvt_pk_bf16_f32 v31, v26, v27
	s_nop 1
	v_permlane16_swap_b32 v28, v30
	v_permlane16_swap_b32 v29, v31
	global_store_dwordx4 v143, v[28:31], s[50:51]
.Luq_skipbj_6_0:
	s_cmp_eq_u32 s47, 0
	s_cbranch_scc1 .Luq_skipbj_6_1
	v_pk_mul_f32 v[20:21], v[20:21], v[164:165] op_sel_hi:[1,0]
	v_pk_mul_f32 v[22:23], v[22:23], v[164:165] op_sel_hi:[1,0]
	s_cmp_eq_u32 s44, 0
	s_cbranch_scc1 .Luq_plain_27
	ds_bpermute_b32 v242, v144, v20
	ds_bpermute_b32 v243, v144, v21
	ds_bpermute_b32 v244, v144, v22
	ds_bpermute_b32 v245, v144, v23
	s_cmp_eq_u32 s44, 1
	s_cbranch_scc0 .Luq_col_27
	s_waitcnt lgkmcnt(0)
	v_pk_mul_f32 v[242:243], v[242:243], v[188:189]
	v_pk_mul_f32 v[244:245], v[244:245], v[190:191]
	v_pk_fma_f32 v[20:21], v[20:21], v[174:175], v[242:243]
	v_pk_fma_f32 v[22:23], v[22:23], v[176:177], v[244:245]
	s_branch .Luq_plain_27
.Luq_col_27:
	s_waitcnt lgkmcnt(0)
	v_pk_mul_f32 v[242:243], v[242:243], v[216:217]
	v_pk_mul_f32 v[244:245], v[244:245], v[218:219]
	v_pk_fma_f32 v[20:21], v[20:21], v[200:201], v[242:243]
	v_pk_fma_f32 v[22:23], v[22:23], v[202:203], v[244:245]
.Luq_plain_27:
	v_pk_mul_f32 v[16:17], v[16:17], v[164:165] op_sel_hi:[1,0]
	v_pk_mul_f32 v[18:19], v[18:19], v[164:165] op_sel_hi:[1,0]
	s_cmp_eq_u32 s45, 0
	s_cbranch_scc1 .Luq_plain_28
	ds_bpermute_b32 v242, v144, v16
	ds_bpermute_b32 v243, v144, v17
	ds_bpermute_b32 v244, v144, v18
	ds_bpermute_b32 v245, v144, v19
	s_cmp_eq_u32 s45, 1
	s_cbranch_scc0 .Luq_col_28
	s_waitcnt lgkmcnt(0)
	v_pk_mul_f32 v[242:243], v[242:243], v[188:189]
	v_pk_mul_f32 v[244:245], v[244:245], v[190:191]
	v_pk_fma_f32 v[16:17], v[16:17], v[174:175], v[242:243]
	v_pk_fma_f32 v[18:19], v[18:19], v[176:177], v[244:245]
	s_branch .Luq_plain_28
.Luq_col_28:
	s_waitcnt lgkmcnt(0)
	v_pk_mul_f32 v[242:243], v[242:243], v[216:217]
	v_pk_mul_f32 v[244:245], v[244:245], v[218:219]
	v_pk_fma_f32 v[16:17], v[16:17], v[200:201], v[242:243]
	v_pk_fma_f32 v[18:19], v[18:19], v[202:203], v[244:245]
.Luq_plain_28:
	v_cvt_pk_bf16_f32 v20, v20, v21
	v_cvt_pk_bf16_f32 v21, v22, v23
	v_cvt_pk_bf16_f32 v22, v16, v17
	v_cvt_pk_bf16_f32 v23, v18, v19
	s_nop 1
	v_permlane16_swap_b32 v20, v22
	v_permlane16_swap_b32 v21, v23
	global_store_dwordx4 v143, v[20:23], s[50:51] offset:256
.Luq_skipbj_6_1:
	s_add_u32 s50, s48, 0x21000
	s_addc_u32 s51, s49, 0
	s_cmp_eq_u32 s46, 0
	s_cbranch_scc1 .Luq_skipbj_7_0
	v_pk_mul_f32 v[12:13], v[12:13], v[164:165] op_sel:[0,1] op_sel_hi:[1,1]
	v_pk_mul_f32 v[14:15], v[14:15], v[164:165] op_sel:[0,1] op_sel_hi:[1,1]
	s_cmp_eq_u32 s42, 0
	s_cbranch_scc1 .Luq_plain_29
	ds_bpermute_b32 v242, v144, v12
	ds_bpermute_b32 v243, v144, v13
	ds_bpermute_b32 v244, v144, v14
	ds_bpermute_b32 v245, v144, v15
	s_cmp_eq_u32 s42, 1
	s_cbranch_scc0 .Luq_col_29
	s_waitcnt lgkmcnt(0)
	v_pk_mul_f32 v[242:243], v[242:243], v[188:189]
	v_pk_mul_f32 v[244:245], v[244:245], v[190:191]
	v_pk_fma_f32 v[12:13], v[12:13], v[174:175], v[242:243]
	v_pk_fma_f32 v[14:15], v[14:15], v[176:177], v[244:245]
	s_branch .Luq_plain_29
.Luq_col_29:
	s_waitcnt lgkmcnt(0)
	v_pk_mul_f32 v[242:243], v[242:243], v[238:239]
	v_pk_mul_f32 v[244:245], v[244:245], v[240:241]
	v_pk_fma_f32 v[12:13], v[12:13], v[204:205], v[242:243]
	v_pk_fma_f32 v[14:15], v[14:15], v[206:207], v[244:245]
.Luq_plain_29:
	v_pk_mul_f32 v[8:9], v[8:9], v[164:165] op_sel:[0,1] op_sel_hi:[1,1]
	v_pk_mul_f32 v[10:11], v[10:11], v[164:165] op_sel:[0,1] op_sel_hi:[1,1]
	s_cmp_eq_u32 s43, 0
	s_cbranch_scc1 .Luq_plain_30
	ds_bpermute_b32 v242, v144, v8
	ds_bpermute_b32 v243, v144, v9
	ds_bpermute_b32 v244, v144, v10
	ds_bpermute_b32 v245, v144, v11
	s_cmp_eq_u32 s43, 1
	s_cbranch_scc0 .Luq_col_30
	s_waitcnt lgkmcnt(0)
	v_pk_mul_f32 v[242:243], v[242:243], v[188:189]
	v_pk_mul_f32 v[244:245], v[244:245], v[190:191]
	v_pk_fma_f32 v[8:9], v[8:9], v[174:175], v[242:243]
	v_pk_fma_f32 v[10:11], v[10:11], v[176:177], v[244:245]
	s_branch .Luq_plain_30
.Luq_col_30:
	s_waitcnt lgkmcnt(0)
	v_pk_mul_f32 v[242:243], v[242:243], v[238:239]
	v_pk_mul_f32 v[244:245], v[244:245], v[240:241]
	v_pk_fma_f32 v[8:9], v[8:9], v[204:205], v[242:243]
	v_pk_fma_f32 v[10:11], v[10:11], v[206:207], v[244:245]
.Luq_plain_30:
	v_cvt_pk_bf16_f32 v12, v12, v13
	v_cvt_pk_bf16_f32 v13, v14, v15
	v_cvt_pk_bf16_f32 v14, v8, v9
	v_cvt_pk_bf16_f32 v15, v10, v11
	s_nop 1
	v_permlane16_swap_b32 v12, v14
	v_permlane16_swap_b32 v13, v15
	global_store_dwordx4 v143, v[12:15], s[50:51]
.Luq_skipbj_7_0:
	s_cmp_eq_u32 s47, 0
	s_cbranch_scc1 .Luq_skipbj_7_1
	v_pk_mul_f32 v[4:5], v[4:5], v[164:165] op_sel:[0,1] op_sel_hi:[1,1]
	v_pk_mul_f32 v[6:7], v[6:7], v[164:165] op_sel:[0,1] op_sel_hi:[1,1]
	s_cmp_eq_u32 s44, 0
	s_cbranch_scc1 .Luq_plain_31
	ds_bpermute_b32 v242, v144, v4
	ds_bpermute_b32 v243, v144, v5
	ds_bpermute_b32 v244, v144, v6
	ds_bpermute_b32 v245, v144, v7
	s_cmp_eq_u32 s44, 1
	s_cbranch_scc0 .Luq_col_31
	s_waitcnt lgkmcnt(0)
	v_pk_mul_f32 v[242:243], v[242:243], v[188:189]
	v_pk_mul_f32 v[244:245], v[244:245], v[190:191]
	v_pk_fma_f32 v[4:5], v[4:5], v[174:175], v[242:243]
	v_pk_fma_f32 v[6:7], v[6:7], v[176:177], v[244:245]
	s_branch .Luq_plain_31
.Luq_col_31:
	s_waitcnt lgkmcnt(0)
	v_pk_mul_f32 v[242:243], v[242:243], v[238:239]
	v_pk_mul_f32 v[244:245], v[244:245], v[240:241]
	v_pk_fma_f32 v[4:5], v[4:5], v[204:205], v[242:243]
	v_pk_fma_f32 v[6:7], v[6:7], v[206:207], v[244:245]
.Luq_plain_31:
	v_pk_mul_f32 v[0:1], v[0:1], v[164:165] op_sel:[0,1] op_sel_hi:[1,1]
	v_pk_mul_f32 v[2:3], v[2:3], v[164:165] op_sel:[0,1] op_sel_hi:[1,1]
	s_cmp_eq_u32 s45, 0
	s_cbranch_scc1 .Luq_plain_32
	ds_bpermute_b32 v242, v144, v0
	ds_bpermute_b32 v243, v144, v1
	ds_bpermute_b32 v244, v144, v2
	ds_bpermute_b32 v245, v144, v3
	s_cmp_eq_u32 s45, 1
	s_cbranch_scc0 .Luq_col_32
	s_waitcnt lgkmcnt(0)
	v_pk_mul_f32 v[242:243], v[242:243], v[188:189]
	v_pk_mul_f32 v[244:245], v[244:245], v[190:191]
	v_pk_fma_f32 v[0:1], v[0:1], v[174:175], v[242:243]
	v_pk_fma_f32 v[2:3], v[2:3], v[176:177], v[244:245]
	s_branch .Luq_plain_32
.Luq_col_32:
	s_waitcnt lgkmcnt(0)
	v_pk_mul_f32 v[242:243], v[242:243], v[238:239]
	v_pk_mul_f32 v[244:245], v[244:245], v[240:241]
	v_pk_fma_f32 v[0:1], v[0:1], v[204:205], v[242:243]
	v_pk_fma_f32 v[2:3], v[2:3], v[206:207], v[244:245]
.Luq_plain_32:
	v_cvt_pk_bf16_f32 v4, v4, v5
	v_cvt_pk_bf16_f32 v5, v6, v7
	v_cvt_pk_bf16_f32 v6, v0, v1
	v_cvt_pk_bf16_f32 v7, v2, v3
	s_nop 1
	v_permlane16_swap_b32 v4, v6
	v_permlane16_swap_b32 v5, v7
	global_store_dwordx4 v143, v[4:7], s[50:51] offset:256
.Luq_skipbj_7_1:
	s_and_b64 vcc, exec, s[40:41]
	s_mov_b64 s[40:41], -1
	s_cbranch_vccnz .LBB0_607
	s_branch .LBB0_748
	v_lshl_add_u32 v172, s24, 8, v155
	v_mov_b32_e32 v142, v172
	v_readlane_b32 s20, v255, 31
	v_readlane_b32 s21, v255, 32
	v_ashrrev_i32_e32 v143, 31, v142
	v_or_b32_e32 v170, 16, v172
	v_lshl_add_u64 v[142:143], v[142:143], 2, s[20:21]
	global_load_dword v98, v[142:143], off
	v_mov_b32_e32 v142, v170
	v_or_b32_e32 v168, 32, v172
	v_ashrrev_i32_e32 v143, 31, v142
	v_lshl_add_u64 v[142:143], v[142:143], 2, s[20:21]
	global_load_dword v171, v[142:143], off
	v_mov_b32_e32 v142, v168
	v_or_b32_e32 v166, 48, v172
	v_ashrrev_i32_e32 v143, 31, v142
	v_lshl_add_u64 v[142:143], v[142:143], 2, s[20:21]
	global_load_dword v169, v[142:143], off
	v_mov_b32_e32 v142, v166
	v_add_u32_e32 v164, 0x80, v172
	v_ashrrev_i32_e32 v143, 31, v142
	v_lshl_add_u64 v[142:143], v[142:143], 2, s[20:21]
	global_load_dword v167, v[142:143], off
	v_mov_b32_e32 v142, v164
	v_add_u32_e32 v162, 0x90, v172
	v_ashrrev_i32_e32 v143, 31, v142
	v_lshl_add_u64 v[142:143], v[142:143], 2, s[20:21]
	global_load_dword v165, v[142:143], off
	v_mov_b32_e32 v142, v162
	v_add_u32_e32 v160, 0xa0, v172
	v_ashrrev_i32_e32 v143, 31, v142
	v_lshl_add_u64 v[142:143], v[142:143], 2, s[20:21]
	global_load_dword v163, v[142:143], off
	v_mov_b32_e32 v142, v160
	v_add_u32_e32 v158, 0xb0, v172
	v_ashrrev_i32_e32 v143, 31, v142
	v_lshl_add_u64 v[142:143], v[142:143], 2, s[20:21]
	global_load_dword v161, v[142:143], off
	v_mov_b32_e32 v142, v158
	s_cmpk_lt_i32 s24, 0x80
	v_ashrrev_i32_e32 v143, 31, v142
	v_lshl_add_u64 v[142:143], v[142:143], 2, s[20:21]
	global_load_dword v159, v[142:143], off
	s_cselect_b64 s[52:53], -1, 0
	s_lshl_b32 s20, s22, 8
	s_or_b32 s50, s20, s66
	s_cmpk_lt_i32 s50, 0x180
	s_cselect_b64 s[44:45], -1, 0
	v_lshrrev_b32_e32 v173, 6, v172
	s_cmpk_gt_i32 s50, 0x17f
	s_waitcnt vmcnt(0)
	v_fmamk_f32 v98, v98, 0x3b800000, v223
	v_cmp_gt_f32_e32 vcc, s29, v98
	v_mul_f32_e32 v142, 0x4b800000, v98
	s_nop 0
	v_cndmask_b32_e32 v98, v98, v142, vcc
	v_rsq_f32_e32 v98, v98
	s_nop 0
	v_mul_f32_e32 v142, 0x45800000, v98
	v_cndmask_b32_e32 v98, v98, v142, vcc
	v_mul_f32_e32 v144, 0x3e16c740, v98
	v_mov_b32_e32 v145, v144
	v_mad_i64_i32 v[142:143], s[24:25], v172, s76, 0
	s_cbranch_scc1 .LBB0_623
	s_ashr_i32 s20, s50, 4
	s_mul_hi_i32 s21, s20, 0x2aaaaaab
	s_lshr_b32 s22, s21, 31
	s_add_i32 s21, s21, s22
	s_mul_i32 s21, s21, 6
	s_sub_i32 s22, s20, s21
	s_cmp_gt_i32 s22, 3
	s_cselect_b64 s[24:25], -1, 0
	v_mov_b32_e32 v174, v144
	v_mov_b32_e32 v175, v144
	s_and_b64 s[24:25], s[52:53], s[24:25]
	v_pk_mul_f32 v[130:131], v[130:131], v[174:175]
	s_andn2_b64 vcc, exec, s[24:25]
	v_pk_mul_f32 v[128:129], v[128:129], v[144:145]
	s_cbranch_vccnz .LBB0_622
	s_cmp_eq_u32 s22, 4
	s_cselect_b64 vcc, -1, 0
	v_cndmask_b32_e32 v98, v172, v173, vcc
	v_lshlrev_b32_e32 v98, 6, v98
	v_and_b32_e32 v98, 0xfc0, v98
	v_lshl_add_u64 v[178:179], v[136:137], 0, v[98:99]
	flat_load_dwordx4 v[174:177], v[178:179]
	flat_load_dwordx4 v[188:191], v[178:179] offset:32
	v_cmp_lt_i32_e32 vcc, v232, v226
	s_nop 1
	v_cndmask_b32_e32 v98, v225, v232, vcc
	v_lshlrev_b32_e32 v98, 2, v98
	ds_bpermute_b32 v178, v98, v128
	ds_bpermute_b32 v179, v98, v129
	s_waitcnt vmcnt(0) lgkmcnt(0)
	v_pk_mul_f32 v[178:179], v[188:189], v[178:179]
	ds_bpermute_b32 v188, v98, v130
	ds_bpermute_b32 v189, v98, v131
	v_cndmask_b32_e64 v179, v179, -v179, s[38:39]
	v_cndmask_b32_e64 v178, v178, -v178, s[38:39]
	v_pk_fma_f32 v[128:129], v[128:129], v[174:175], v[178:179]
	s_waitcnt lgkmcnt(0)
	v_pk_mul_f32 v[188:189], v[190:191], v[188:189]
	s_nop 0
	v_cndmask_b32_e64 v189, v189, -v189, s[38:39]
	v_cndmask_b32_e64 v188, v188, -v188, s[38:39]
	v_pk_fma_f32 v[130:131], v[130:131], v[176:177], v[188:189]
